# loop-edge: the attention exit stub falls through into the RNN entry (redundant s_branch removed)
# speedup vs baseline: 1.0033x; 1.0033x over previous
.Lattn_exit:
	s_barrier
.LBB0_359:
	v_readlane_b32 s68, v255, 12
	v_readlane_b32 s88, v255, 10
	s_cmpk_gt_i32 s97, 0xff
	v_readlane_b32 s69, v255, 13
	v_readlane_b32 s89, v255, 11
	s_cbranch_scc1 .LBB0_410
	v_lshrrev_b32_e32 v48, 3, v251
	v_and_b32_e32 v1, 7, v251
	v_lshlrev_b32_e32 v50, 7, v48
	v_mov_b32_e32 v51, 0
	v_lshlrev_b32_e32 v2, 4, v1
	v_mov_b32_e32 v3, v51
	v_lshl_add_u64 v[4:5], s[84:85], 0, v[50:51]
	v_and_b32_e32 v49, 63, v251
	v_lshl_add_u64 v[4:5], v[4:5], 0, v[2:3]
	s_mov_b64 s[0:1], 0x100000
	s_mov_b64 s[2:3], 0x120000
	v_lshl_add_u64 v[52:53], v[4:5], 0, s[0:1]
	v_lshl_add_u64 v[54:55], v[4:5], 0, s[2:3]
	v_and_b32_e32 v3, 48, v251
	s_add_i32 s1, 0, 0x19400
	v_lshlrev_b32_e32 v4, 2, v49
	v_lshlrev_b32_e32 v87, 1, v49
	v_add_u32_e32 v89, s1, v4
	v_add_u32_e32 v90, 0, v3
	v_lshrrev_b32_e32 v3, 2, v251
	s_add_i32 s1, 0, 0x19800
	v_and_b32_e32 v91, 12, v3
	v_add_u32_e32 v92, s1, v87
	v_mov_b32_e32 v3, s1
	s_add_i32 s1, 0, 0x18400
	v_or_b32_e32 v5, 0x100, v4
	s_add_i32 s21, 0, 0x18c00
	v_add_u32_e32 v93, s1, v5
	v_add_u32_e32 v94, s21, v5
	v_or_b32_e32 v5, 0x200, v4
	v_add_u32_e32 v95, s1, v5
	v_add_u32_e32 v96, s21, v5
	v_or_b32_e32 v5, 0x300, v4
	v_add_u32_e32 v97, s1, v5
	v_add_u32_e32 v98, s21, v5
	v_or_b32_e32 v5, 0x400, v4
	s_movk_i32 s0, 0x90
	v_add_u32_e32 v99, s1, v5
	v_add_u32_e32 v100, s21, v5
	v_or_b32_e32 v5, 0x500, v4
	v_lshlrev_b32_e32 v0, 3, v1
	v_mad_u32_u24 v1, v48, s0, 0
	v_and_b32_e32 v86, 15, v251
	v_mad_u32_u24 v3, v48, s0, v3
	v_add_u32_e32 v101, s1, v5
	v_add_u32_e32 v102, s21, v5
	v_or_b32_e32 v5, 0x600, v4
	v_lshl_or_b32 v50, v48, 12, v2
	s_mov_b32 s19, 0
	v_add_u32_e32 v88, 0, v87
	v_add_u32_e32 v103, s1, v5
	v_add_u32_e32 v104, s21, v5
	v_add_u32_e32 v105, s21, v4
	v_add_u32_e32 v106, s1, v4
	v_or_b32_e32 v107, 16, v86
	v_add_u32_e32 v108, 0x44, v86
	v_add_u32_e32 v109, 0x44, v49
	v_lshl_add_u64 v[56:57], s[84:85], 0, v[50:51]
	v_add_u32_e32 v110, v1, v2
	s_mov_b32 s23, 0xbfb8aa3b
	s_mov_b32 s25, 0x42ce8ed0
	s_mov_b32 s33, 0xc2b17218
	s_mov_b32 s36, 0x7f800000
	v_mov_b32_e32 v111, 0x7f800000
	s_mov_b32 s37, 0x3f2aaaab
	v_mov_b32_e32 v112, 0x3ecc95a3
	s_mov_b32 s54, 0x3f317218
	s_mov_b32 s55, 0x33800000
	s_mov_b32 s64, 0x40000
	s_mov_b32 s65, 0x80000
	s_add_i32 s76, 0, 0x14000
	s_mov_b32 s20, 0x3fb8aa3b
	s_mov_b32 s22, 0x3dd2d3e8
	s_mov_b32 s24, 0xc0135761
	v_mov_b32_e32 v58, 0x3f317218
	v_lshlrev_b32_e32 v60, 1, v0
	v_mov_b32_e32 v61, v51
	v_add_u32_e32 v113, v3, v2
	s_mov_b32 s77, s97
	s_mov_b32 s78, s97
	s_branch .LBB0_362
